# GLA p2 layer0 second-direction loop: next chunk q/k/v fetched during the output/state-update stage of the previous chunk
# speedup vs baseline: 1.0022x; 1.0022x over previous
.LBB0_678:
	s_or_b64 exec, exec, s[54:55]
	s_lshl_b32 s48, s90, 2
	v_lshl_add_u64 v[134:135], v[132:133], 0, s[48:49]
	v_readlane_b32 s48, v240, 23
	s_add_u32 s48, s48, s68
	v_readlane_b32 s54, v240, 25
	s_addc_u32 s55, s54, 0
	s_add_i32 s54, s56, 0x140
	s_add_u32 s48, s48, s58
	s_addc_u32 s55, s55, s59
	s_add_u32 s56, s48, 0xe0000
	s_addc_u32 s57, s55, 0
	s_add_u32 s48, s73, s58
	s_addc_u32 s55, s86, s59
	s_add_u32 s58, s48, 0xe0000
	s_addc_u32 s59, s55, 0
	s_add_u32 s48, s53, s88
	s_addc_u32 s70, s51, s87
	s_add_u32 s55, s67, s88
	s_addc_u32 s60, s72, s87
	s_add_u32 s71, s55, 0x2a0000
	s_addc_u32 s74, s60, 0
	s_mov_b32 s75, 0
	s_mov_b64 s[60:61], 0
	s_waitcnt lgkmcnt(0)
	s_barrier
	s_add_u32 s62, s71, s60
	s_addc_u32 s63, s74, s61
	s_add_u32 s72, s48, s60
	s_addc_u32 s73, s70, s61
	s_add_u32 s55, s72, s68
	v_lshl_add_u64 v[232:233], s[62:63], 0, v[112:113]
	s_addc_u32 s63, s73, 0
	s_add_u32 s62, s55, 0xafc0800
	v_add_co_u32_e32 v244, vcc, s95, v232
	s_addc_u32 s63, s63, 0
	s_nop 0
	v_addc_co_u32_e32 v245, vcc, 0, v233, vcc
	v_lshl_add_u64 v[170:171], s[62:63], 0, v[114:115]
	v_add_co_u32_e32 v248, vcc, s81, v170
	s_nop 0
	v_addc_co_u32_e32 v249, vcc, 0, v171, vcc
	v_add_co_u32_e32 v252, vcc, s95, v170
	s_nop 0
	v_addc_co_u32_e32 v253, vcc, 0, v171, vcc
	global_load_dwordx4 v[192:195], v[232:233], off
	global_load_dwordx4 v[196:199], v[232:233], off offset:1024
	s_nop 0
	global_load_dwordx4 v[232:235], v[244:245], off
	global_load_dwordx4 v[236:239], v[244:245], off offset:1024
	global_load_dwordx4 v[244:247], v[170:171], off
	v_add_co_u32_e32 v170, vcc, s96, v170
	s_nop 0
	v_addc_co_u32_e32 v171, vcc, 0, v171, vcc
	global_load_dwordx4 v[248:251], v[248:249], off
	s_nop 0
	global_load_dwordx4 v[252:255], v[252:253], off
	s_nop 0
	global_load_dwordx4 v[170:173], v[170:171], off
	s_waitcnt vmcnt(8)
	s_branch .LBB0_680
.LBB0_679:
	s_or_b64 exec, exec, s[62:63]
	s_waitcnt lgkmcnt(0)
	s_barrier
	ds_read_b128 v[136:139], v184
	ds_read_b128 v[142:145], v184 offset:16
	s_waitcnt vmcnt(8)
	v_lshlrev_b32_e32 v156, 16, v166
	v_and_b32_e32 v157, 0xffff0000, v166
	v_lshlrev_b32_e32 v166, 16, v167
	s_waitcnt lgkmcnt(1)
	v_mov_b32_e32 v81, v138
	v_lshlrev_b32_e32 v138, 16, v168
	v_mov_b32_e32 v80, v137
	v_mov_b32_e32 v137, v139
	v_and_b32_e32 v139, 0xffff0000, v168
	v_mul_f32_e32 v0, 0xbfb8aa3b, v138
	v_pk_add_f32 v[80:81], v[80:81], v[136:137]
	s_waitcnt lgkmcnt(0)
	v_mov_b32_e32 v136, v144
	v_exp_f32_e32 v0, v0
	v_mul_f32_e32 v144, 0xbfb8aa3b, v139
	v_exp_f32_e32 v144, v144
	v_mov_b32_e32 v137, v142
	v_mov_b32_e32 v142, v145
	v_add_f32_e32 v0, 1.0, v0
	v_pk_add_f32 v[146:147], v[136:137], v[142:143]
	v_rcp_f32_e32 v136, v0
	v_add_f32_e32 v0, 1.0, v144
	v_lshlrev_b32_e32 v142, 16, v169
	v_rcp_f32_e32 v137, v0
	v_and_b32_e32 v143, 0xffff0000, v169
	v_mul_f32_e32 v0, 0xbfb8aa3b, v142
	v_exp_f32_e32 v0, v0
	v_mul_f32_e32 v144, 0xbfb8aa3b, v143
	v_exp_f32_e32 v144, v144
	v_pk_mul_f32 v[148:149], v[136:137], v[138:139]
	v_add_f32_e32 v0, 1.0, v0
	v_rcp_f32_e32 v136, v0
	v_add_f32_e32 v0, 1.0, v144
	v_rcp_f32_e32 v137, v0
	v_mul_f32_e32 v0, 0xbfb8aa3b, v156
	v_exp_f32_e32 v0, v0
	v_mul_f32_e32 v138, 0xbfb8aa3b, v157
	v_exp_f32_e32 v138, v138
	v_and_b32_e32 v167, 0xffff0000, v167
	v_add_f32_e32 v0, 1.0, v0
	v_rcp_f32_e32 v224, v0
	v_add_f32_e32 v0, 1.0, v138
	v_rcp_f32_e32 v225, v0
	v_mul_f32_e32 v0, 0xbfb8aa3b, v166
	v_pk_mul_f32 v[168:169], v[136:137], v[142:143]
	v_exp_f32_e32 v0, v0
	v_mul_f32_e32 v136, 0xbfb8aa3b, v167
	v_exp_f32_e32 v142, v136
	ds_read_b128 v[136:139], v184 offset:512
	v_add_f32_e32 v0, 1.0, v0
	v_rcp_f32_e32 v226, v0
	v_add_f32_e32 v0, 1.0, v142
	ds_read_b128 v[142:145], v184 offset:528
	s_waitcnt lgkmcnt(1)
	v_mov_b32_e32 v228, v137
	v_mov_b32_e32 v229, v138
	v_mov_b32_e32 v137, v139
	v_pk_add_f32 v[136:137], v[228:229], v[136:137]
	s_waitcnt lgkmcnt(0)
	v_mov_b32_e32 v138, v144
	v_mov_b32_e32 v139, v142
	v_mov_b32_e32 v142, v145
	v_pk_add_f32 v[138:139], v[138:139], v[142:143]
	v_mov_b32_e32 v142, v136
	v_mov_b32_e32 v143, v80
	v_mov_b32_e32 v80, v137
	v_pk_add_f32 v[80:81], v[142:143], v[80:81]
	v_mov_b32_e32 v136, v139
	v_mov_b32_e32 v137, v147
	v_pk_add_f32 v[80:81], v[80:81], v[136:137]
	v_mov_b32_e32 v139, v146
	s_mov_b32 s62, 0x358637bd
	v_pk_add_f32 v[136:137], v[138:139], v[80:81]
	v_mov_b64_e32 v[80:81], s[62:63]
	v_pk_fma_f32 v[136:137], v[136:137], s[52:53], v[80:81] op_sel_hi:[1,0,0]
	v_rcp_f32_e32 v227, v0
	v_mul_f32_e32 v0, 0x4b800000, v137
	v_cmp_gt_f32_e32 vcc, s1, v137
	v_pk_mul_f32 v[142:143], v[224:225], v[156:157]
	v_pk_mul_f32 v[144:145], v[226:227], v[166:167]
	v_cndmask_b32_e32 v0, v137, v0, vcc
	v_rsq_f32_e32 v0, v0
	v_lshl_add_u64 v[138:139], s[56:57], 0, v[116:117]
	s_waitcnt vmcnt(4)
	v_lshlrev_b32_e32 v146, 16, v159
	v_and_b32_e32 v147, 0xffff0000, v159
	v_mul_f32_e32 v137, 0x45800000, v0
	v_cndmask_b32_e32 v0, v0, v137, vcc
	v_pk_mul_f32 v[106:107], v[106:107], v[0:1] op_sel_hi:[1,0]
	v_pk_mul_f32 v[108:109], v[108:109], v[0:1] op_sel_hi:[1,0]
	v_pk_mul_f32 v[102:103], v[102:103], v[0:1] op_sel_hi:[1,0]
	v_pk_mul_f32 v[104:105], v[104:105], v[0:1] op_sel_hi:[1,0]
	v_mul_f32_e32 v0, 0x4b800000, v136
	v_cmp_gt_f32_e32 vcc, s1, v136
	s_waitcnt vmcnt(0)
	v_pk_mul_f32 v[102:103], v[70:71], v[102:103]
	v_pk_mul_f32 v[104:105], v[72:73], v[104:105]
	v_cndmask_b32_e32 v0, v136, v0, vcc
	v_pk_mul_f32 v[102:103], v[142:143], v[102:103]
	v_pk_mul_f32 v[104:105], v[144:145], v[104:105]
	v_rsq_f32_e32 v0, v0
	v_cvt_pk_bf16_f32 v102, v102, v103
	v_cvt_pk_bf16_f32 v103, v104, v105
	global_store_dwordx2 v[138:139], v[102:103], off offset:32
	v_lshlrev_b32_e32 v102, 16, v164
	v_mul_f32_e32 v103, 0xbfb8aa3b, v102
	v_exp_f32_e32 v104, v103
	v_mul_f32_e32 v103, 0x45800000, v0
	v_cndmask_b32_e32 v0, v0, v103, vcc
	v_and_b32_e32 v103, 0xffff0000, v164
	v_mul_f32_e32 v105, 0xbfb8aa3b, v103
	v_exp_f32_e32 v105, v105
	v_pk_mul_f32 v[106:107], v[74:75], v[106:107]
	v_pk_mul_f32 v[108:109], v[76:77], v[108:109]
	v_pk_mul_f32 v[106:107], v[148:149], v[106:107]
	v_pk_mul_f32 v[108:109], v[168:169], v[108:109]
	v_cvt_pk_bf16_f32 v106, v106, v107
	v_cvt_pk_bf16_f32 v107, v108, v109
	v_lshlrev_b32_e32 v108, 16, v165
	v_and_b32_e32 v109, 0xffff0000, v165
	v_add_f32_e32 v104, 1.0, v104
	v_add_f32_e32 v105, 1.0, v105
	v_mul_f32_e32 v136, 0xbfb8aa3b, v108
	v_mul_f32_e32 v137, 0xbfb8aa3b, v109
	v_rcp_f32_e32 v104, v104
	v_rcp_f32_e32 v105, v105
	v_exp_f32_e32 v136, v136
	v_exp_f32_e32 v137, v137
	global_store_dwordx2 v[138:139], v[106:107], off
	v_pk_mul_f32 v[102:103], v[104:105], v[102:103]
	v_add_f32_e32 v104, 1.0, v136
	v_add_f32_e32 v105, 1.0, v137
	v_rcp_f32_e32 v104, v104
	v_rcp_f32_e32 v105, v105
	v_pk_mul_f32 v[106:107], v[152:153], v[0:1] op_sel_hi:[1,0]
	v_pk_mul_f32 v[100:101], v[100:101], v[0:1] op_sel_hi:[1,0]
	v_pk_mul_f32 v[106:107], v[74:75], v[106:107]
	v_pk_mul_f32 v[100:101], v[76:77], v[100:101]
	v_pk_mul_f32 v[104:105], v[104:105], v[108:109]
	v_pk_mul_f32 v[102:103], v[102:103], v[106:107]
	v_pk_mul_f32 v[100:101], v[104:105], v[100:101]
	v_cvt_pk_bf16_f32 v102, v102, v103
	v_cvt_pk_bf16_f32 v103, v100, v101
	v_lshlrev_b32_e32 v100, 16, v162
	v_mul_f32_e32 v101, 0xbfb8aa3b, v100
	v_exp_f32_e32 v106, v101
	v_lshl_add_u64 v[104:105], s[56:57], 0, v[120:121]
	v_and_b32_e32 v101, 0xffff0000, v162
	global_store_dwordx2 v[104:105], v[102:103], off
	v_mul_f32_e32 v103, 0xbfb8aa3b, v101
	v_exp_f32_e32 v103, v103
	v_lshlrev_b32_e32 v104, 16, v163
	v_and_b32_e32 v105, 0xffff0000, v163
	v_add_f32_e32 v102, 1.0, v106
	v_add_f32_e32 v103, 1.0, v103
	v_mul_f32_e32 v106, 0xbfb8aa3b, v104
	v_mul_f32_e32 v107, 0xbfb8aa3b, v105
	v_rcp_f32_e32 v102, v102
	v_rcp_f32_e32 v103, v103
	v_exp_f32_e32 v106, v106
	v_exp_f32_e32 v107, v107
	v_pk_mul_f32 v[98:99], v[98:99], v[0:1] op_sel_hi:[1,0]
	v_pk_mul_f32 v[100:101], v[102:103], v[100:101]
	v_add_f32_e32 v102, 1.0, v106
	v_add_f32_e32 v103, 1.0, v107
	v_rcp_f32_e32 v102, v102
	v_rcp_f32_e32 v103, v103
	v_pk_mul_f32 v[98:99], v[70:71], v[98:99]
	v_pk_mul_f32 v[96:97], v[96:97], v[0:1] op_sel_hi:[1,0]
	v_pk_mul_f32 v[98:99], v[100:101], v[98:99]
	v_pk_mul_f32 v[96:97], v[72:73], v[96:97]
	v_pk_mul_f32 v[100:101], v[102:103], v[104:105]
	v_cvt_pk_bf16_f32 v102, v98, v99
	v_pk_mul_f32 v[100:101], v[100:101], v[96:97]
	ds_read_b128 v[96:99], v184 offset:1024
	v_cvt_pk_bf16_f32 v103, v100, v101
	v_lshl_add_u64 v[100:101], s[56:57], 0, v[122:123]
	global_store_dwordx2 v[100:101], v[102:103], off
	ds_read_b128 v[100:103], v184 offset:1040
	s_waitcnt lgkmcnt(1)
	v_mov_b32_e32 v105, v98
	v_lshlrev_b32_e32 v98, 16, v160
	v_mov_b32_e32 v104, v97
	v_mov_b32_e32 v97, v99
	v_and_b32_e32 v99, 0xffff0000, v160
	v_mul_f32_e32 v0, 0xbfb8aa3b, v98
	v_pk_add_f32 v[104:105], v[104:105], v[96:97]
	v_exp_f32_e32 v0, v0
	v_mul_f32_e32 v97, 0xbfb8aa3b, v99
	s_waitcnt lgkmcnt(0)
	v_mov_b32_e32 v96, v102
	v_exp_f32_e32 v102, v97
	v_lshlrev_b32_e32 v108, 16, v161
	v_mov_b32_e32 v97, v100
	v_add_f32_e32 v0, 1.0, v0
	v_and_b32_e32 v109, 0xffff0000, v161
	v_mul_f32_e32 v100, 0xbfb8aa3b, v108
	v_rcp_f32_e32 v106, v0
	v_add_f32_e32 v0, 1.0, v102
	v_exp_f32_e32 v100, v100
	v_mul_f32_e32 v102, 0xbfb8aa3b, v109
	v_exp_f32_e32 v102, v102
	v_rcp_f32_e32 v107, v0
	v_add_f32_e32 v0, 1.0, v100
	v_rcp_f32_e32 v136, v0
	v_add_f32_e32 v0, 1.0, v102
	v_rcp_f32_e32 v137, v0
	v_mov_b32_e32 v100, v103
	v_pk_add_f32 v[138:139], v[96:97], v[100:101]
	v_pk_mul_f32 v[106:107], v[106:107], v[98:99]
	v_pk_mul_f32 v[108:109], v[136:137], v[108:109]
	v_lshlrev_b32_e32 v136, 16, v158
	v_and_b32_e32 v137, 0xffff0000, v158
	v_mul_f32_e32 v0, 0xbfb8aa3b, v136
	v_exp_f32_e32 v0, v0
	v_mul_f32_e32 v96, 0xbfb8aa3b, v137
	v_exp_f32_e32 v96, v96
	v_lshl_add_u64 v[142:143], s[56:57], 0, v[124:125]
	v_add_f32_e32 v0, 1.0, v0
	v_rcp_f32_e32 v144, v0
	v_add_f32_e32 v0, 1.0, v96
	v_rcp_f32_e32 v145, v0
	v_mul_f32_e32 v0, 0xbfb8aa3b, v146
	v_exp_f32_e32 v0, v0
	v_mul_f32_e32 v96, 0xbfb8aa3b, v147
	v_exp_f32_e32 v100, v96
	ds_read_b128 v[96:99], v184 offset:1536
	v_add_f32_e32 v0, 1.0, v0
	v_rcp_f32_e32 v148, v0
	v_add_f32_e32 v0, 1.0, v100
	ds_read_b128 v[100:103], v184 offset:1552
	s_waitcnt lgkmcnt(1)
	v_mov_b32_e32 v152, v97
	v_mov_b32_e32 v153, v98
	v_mov_b32_e32 v97, v99
	v_pk_add_f32 v[96:97], v[152:153], v[96:97]
	s_waitcnt lgkmcnt(0)
	v_mov_b32_e32 v98, v102
	v_mov_b32_e32 v99, v100
	v_mov_b32_e32 v100, v103
	v_pk_add_f32 v[98:99], v[98:99], v[100:101]
	v_mov_b32_e32 v100, v96
	v_mov_b32_e32 v101, v104
	v_mov_b32_e32 v104, v97
	v_pk_add_f32 v[96:97], v[100:101], v[104:105]
	v_mov_b32_e32 v100, v99
	v_mov_b32_e32 v101, v139
	v_pk_add_f32 v[96:97], v[96:97], v[100:101]
	v_mov_b32_e32 v99, v138
	v_pk_add_f32 v[96:97], v[98:99], v[96:97]
	v_rcp_f32_e32 v149, v0
	v_pk_fma_f32 v[80:81], v[96:97], s[52:53], v[80:81] op_sel_hi:[1,0,0]
	v_pk_mul_f32 v[96:97], v[144:145], v[136:137]
	v_mul_f32_e32 v0, 0x4b800000, v81
	v_cmp_gt_f32_e32 vcc, s1, v81
	v_pk_mul_f32 v[152:153], v[148:149], v[146:147]
	v_lshl_add_u64 v[168:169], s[56:57], 0, v[126:127]
	v_cndmask_b32_e32 v0, v81, v0, vcc
	v_rsq_f32_e32 v0, v0
	s_add_i32 s75, s75, 1
	s_add_u32 s60, s60, 0xfffa0000
	s_addc_u32 s61, s61, -1
	v_mul_f32_e32 v81, 0x45800000, v0
	v_cndmask_b32_e32 v0, v0, v81, vcc
	v_pk_mul_f32 v[90:91], v[90:91], v[0:1] op_sel_hi:[1,0]
	v_pk_mul_f32 v[94:95], v[94:95], v[0:1] op_sel_hi:[1,0]
	v_pk_mul_f32 v[90:91], v[74:75], v[90:91]
	v_pk_mul_f32 v[94:95], v[76:77], v[94:95]
	v_pk_mul_f32 v[90:91], v[106:107], v[90:91]
	v_pk_mul_f32 v[94:95], v[108:109], v[94:95]
	v_cvt_pk_bf16_f32 v90, v90, v91
	v_cvt_pk_bf16_f32 v91, v94, v95
	global_store_dwordx2 v[142:143], v[90:91], off
	s_cmp_lt_u32 s75, 8
	s_cselect_b32 s98, 0, 0x60000
	s_cselect_b32 s99, 0, 0
	s_add_u32 s98, s98, s60
	s_addc_u32 s99, s99, s61
	s_add_u32 s62, s71, s98
	s_addc_u32 s63, s74, s99
	s_add_u32 s100, s48, s98
	s_addc_u32 s101, s70, s99
	s_add_u32 s55, s100, s68
	v_lshl_add_u64 v[232:233], s[62:63], 0, v[112:113]
	s_addc_u32 s63, s101, 0
	s_add_u32 s62, s55, 0xafc0800
	v_add_co_u32_e32 v244, vcc, s95, v232
	s_addc_u32 s63, s63, 0
	s_nop 0
	v_addc_co_u32_e32 v245, vcc, 0, v233, vcc
	v_lshl_add_u64 v[170:171], s[62:63], 0, v[114:115]
	v_add_co_u32_e32 v248, vcc, s81, v170
	s_nop 0
	v_addc_co_u32_e32 v249, vcc, 0, v171, vcc
	v_add_co_u32_e32 v252, vcc, s95, v170
	s_nop 0
	v_addc_co_u32_e32 v253, vcc, 0, v171, vcc
	global_load_dwordx4 v[192:195], v[232:233], off
	global_load_dwordx4 v[196:199], v[232:233], off offset:1024
	s_nop 0
	global_load_dwordx4 v[232:235], v[244:245], off
	global_load_dwordx4 v[236:239], v[244:245], off offset:1024
	global_load_dwordx4 v[244:247], v[170:171], off
	v_add_co_u32_e32 v170, vcc, s96, v170
	s_nop 0
	v_addc_co_u32_e32 v171, vcc, 0, v171, vcc
	global_load_dwordx4 v[248:251], v[248:249], off
	s_nop 0
	global_load_dwordx4 v[252:255], v[252:253], off
	s_nop 0
	global_load_dwordx4 v[170:173], v[170:171], off
	v_pk_mul_f32 v[90:91], v[92:93], v[0:1] op_sel_hi:[1,0]
	v_pk_mul_f32 v[88:89], v[88:89], v[0:1] op_sel_hi:[1,0]
	v_mul_f32_e32 v0, 0x4b800000, v80
	v_cmp_gt_f32_e32 vcc, s1, v80
	v_pk_mul_f32 v[90:91], v[70:71], v[90:91]
	v_pk_mul_f32 v[224:225], v[72:73], v[88:89]
	v_cndmask_b32_e32 v0, v80, v0, vcc
	v_pk_mul_f32 v[108:109], v[96:97], v[90:91]
	ds_read_b64_tr_b16 v[90:91], v213 offset:57408
	ds_read_b64_tr_b16 v[88:89], v213 offset:56320
	ds_read_b64_tr_b16 v[94:95], v210 offset:2112
	ds_read_b64_tr_b16 v[92:93], v210
	ds_read_b64_tr_b16 v[98:99], v210 offset:2144
	ds_read_b64_tr_b16 v[96:97], v210 offset:32
	ds_read_b64_tr_b16 v[100:101], v213 offset:56352
	ds_read_b64_tr_b16 v[104:105], v213 offset:56384
	ds_read_b64_tr_b16 v[136:137], v213 offset:56416
	ds_read_b64_tr_b16 v[102:103], v213 offset:57440
	ds_read_b64_tr_b16 v[106:107], v213 offset:57472
	ds_read_b64_tr_b16 v[138:139], v213 offset:57504
	v_rsq_f32_e32 v0, v0
	ds_read_b64_tr_b16 v[142:143], v213 offset:65024
	ds_read_b64_tr_b16 v[144:145], v214 offset:57408
	ds_read_b64_tr_b16 v[146:147], v210 offset:16896
	ds_read_b64_tr_b16 v[148:149], v210 offset:19008
	ds_read_b64_tr_b16 v[158:159], v210 offset:19040
	ds_read_b64_tr_b16 v[156:157], v210 offset:16928
	s_waitcnt lgkmcnt(8)
	v_mfma_f32_16x16x32_bf16 v[10:13], v[100:103], v[92:95], v[10:13]
	v_and_b32_e32 v81, 0xffff0000, v150
	v_mul_f32_e32 v80, 0x45800000, v0
	v_cndmask_b32_e32 v0, v0, v80, vcc
	v_mfma_f32_16x16x32_bf16 v[18:21], v[100:103], v[96:99], v[18:21]
	v_lshlrev_b32_e32 v80, 16, v150
	v_mul_f32_e32 v100, 0xbfb8aa3b, v80
	v_mul_f32_e32 v101, 0xbfb8aa3b, v81
	v_mfma_f32_16x16x32_bf16 v[30:33], v[88:91], v[92:95], v[30:33]
	v_exp_f32_e32 v100, v100
	v_pk_mul_f32 v[86:87], v[86:87], v[0:1] op_sel_hi:[1,0]
	v_pk_mul_f32 v[152:153], v[152:153], v[224:225]
	v_mfma_f32_16x16x32_bf16 v[6:9], v[88:91], v[96:99], v[6:9]
	ds_read_b64_tr_b16 v[88:89], v213 offset:65056
	ds_read_b64_tr_b16 v[160:161], v213 offset:65088
	ds_read_b64_tr_b16 v[164:165], v213 offset:65120
	ds_read_b64_tr_b16 v[90:91], v214 offset:57440
	ds_read_b64_tr_b16 v[162:163], v214 offset:57472
	ds_read_b64_tr_b16 v[166:167], v214 offset:57504
	v_pk_mul_f32 v[74:75], v[74:75], v[86:87]
	v_lshlrev_b32_e32 v86, 16, v151
	s_waitcnt lgkmcnt(2)
	v_mfma_f32_16x16x32_bf16 v[10:13], v[88:91], v[146:149], v[10:13]
	v_mul_f32_e32 v87, 0xbfb8aa3b, v86
	v_cvt_pk_bf16_f32 v108, v108, v109
	v_cvt_pk_bf16_f32 v109, v152, v153
	v_mfma_f32_16x16x32_bf16 v[18:21], v[88:91], v[156:159], v[18:21]
	v_exp_f32_e32 v89, v101
	v_add_f32_e32 v88, 1.0, v100
	v_rcp_f32_e32 v88, v88
	global_store_dwordx2 v[168:169], v[108:109], off
	v_add_f32_e32 v89, 1.0, v89
	v_rcp_f32_e32 v89, v89
	v_mfma_f32_16x16x32_bf16 v[14:17], v[104:107], v[92:95], v[14:17]
	v_mul_f32_e64 v82, v82, v0
	v_mul_f32_e64 v83, v83, v0
	v_pk_mul_f32 v[78:79], v[78:79], v[0:1] op_sel_hi:[1,0]
	v_pk_mul_f32 v[80:81], v[88:89], v[80:81]
	v_exp_f32_e32 v88, v87
	v_pk_mul_f32 v[80:81], v[80:81], v[74:75]
	v_and_b32_e32 v87, 0xffff0000, v151
	v_mfma_f32_16x16x32_bf16 v[26:29], v[104:107], v[96:99], v[26:29]
	v_add_f32_e32 v74, 1.0, v88
	v_rcp_f32_e32 v88, v74
	v_mul_f32_e32 v74, 0xbfb8aa3b, v87
	v_exp_f32_e32 v89, v74
	v_pk_mul_f32 v[74:75], v[84:85], v[0:1] op_sel_hi:[1,0]
	v_mfma_f32_16x16x32_bf16 v[38:41], v[136:139], v[92:95], v[38:41]
	v_mul_f32_e64 v108, v76, v74
	v_mul_f32_e64 v109, v77, v75
	v_add_f32_e32 v74, 1.0, v89
	v_rcp_f32_e32 v89, v74
	ds_read_b64_tr_b16 v[74:75], v213 offset:56448
	ds_read_b64_tr_b16 v[76:77], v213 offset:57536
	v_mfma_f32_16x16x32_bf16 v[50:53], v[136:139], v[96:99], v[50:53]
	v_cvt_pk_bf16_f32 v80, v80, v81
	v_pk_mul_f32 v[136:137], v[88:89], v[86:87]
	ds_read_b64_tr_b16 v[84:85], v213 offset:56480
	ds_read_b64_tr_b16 v[88:89], v213 offset:56512
	ds_read_b64_tr_b16 v[100:101], v213 offset:56544
	ds_read_b64_tr_b16 v[86:87], v213 offset:57568
	ds_read_b64_tr_b16 v[90:91], v213 offset:57600
	ds_read_b64_tr_b16 v[102:103], v213 offset:57632
	ds_read_b64_tr_b16 v[104:105], v213 offset:65152
	ds_read_b64_tr_b16 v[106:107], v214 offset:57536
	s_waitcnt lgkmcnt(8)
	v_mfma_f32_16x16x32_bf16 v[22:25], v[74:77], v[92:95], v[22:25]
	v_mul_f32_e64 v108, v136, v108
	v_mul_f32_e64 v109, v137, v109
	v_pk_mul_f32 v[70:71], v[70:71], v[82:83]
	v_cvt_pk_bf16_f32 v81, v108, v109
	v_mfma_f32_16x16x32_bf16 v[34:37], v[74:77], v[96:99], v[34:37]
	v_lshl_add_u64 v[108:109], s[56:57], 0, v[128:129]
	v_pk_mul_f32 v[72:73], v[72:73], v[78:79]
	v_lshl_add_u32 v0, s67, 9, v179
	v_mfma_f32_16x16x32_bf16 v[30:33], v[142:145], v[146:149], v[30:33]
	s_sub_i32 s54, s54, 64
	v_mfma_f32_16x16x32_bf16 v[6:9], v[142:145], v[156:159], v[6:9]
	ds_read_b64_tr_b16 v[74:75], v213 offset:65184
	ds_read_b64_tr_b16 v[136:137], v213 offset:65216
	ds_read_b64_tr_b16 v[142:143], v213 offset:65248
	ds_read_b64_tr_b16 v[76:77], v214 offset:57568
	ds_read_b64_tr_b16 v[138:139], v214 offset:57600
	ds_read_b64_tr_b16 v[144:145], v214 offset:57632
	global_store_dwordx2 v[108:109], v[80:81], off
	v_lshlrev_b32_e32 v80, 16, v140
	v_and_b32_e32 v81, 0xffff0000, v140
	s_waitcnt lgkmcnt(6)
	v_mfma_f32_16x16x32_bf16 v[22:25], v[104:107], v[146:149], v[22:25]
	v_mfma_f32_16x16x32_bf16 v[34:37], v[104:107], v[156:159], v[34:37]
	v_mul_f32_e32 v104, 0xbfb8aa3b, v80
	v_mul_f32_e32 v105, 0xbfb8aa3b, v81
	v_exp_f32_e32 v104, v104
	v_mfma_f32_16x16x32_bf16 v[42:45], v[84:87], v[92:95], v[42:45]
	v_mfma_f32_16x16x32_bf16 v[54:57], v[84:87], v[96:99], v[54:57]
	v_exp_f32_e32 v85, v105
	v_add_f32_e32 v84, 1.0, v104
	v_rcp_f32_e32 v84, v84
	s_waitcnt lgkmcnt(2)
	v_mfma_f32_16x16x32_bf16 v[42:45], v[74:77], v[146:149], v[42:45]
	v_add_f32_e32 v85, 1.0, v85
	v_rcp_f32_e32 v85, v85
	v_mfma_f32_16x16x32_bf16 v[54:57], v[74:77], v[156:159], v[54:57]
	v_mul_f32_e64 v74, v84, v80
	v_mul_f32_e64 v75, v85, v81
	v_pk_mul_f32 v[70:71], v[74:75], v[70:71]
	v_lshlrev_b32_e32 v74, 16, v141
	v_and_b32_e32 v75, 0xffff0000, v141
	v_mul_f32_e32 v76, 0xbfb8aa3b, v74
	v_mul_f32_e32 v77, 0xbfb8aa3b, v75
	v_exp_f32_e32 v76, v76
	v_exp_f32_e32 v77, v77
	v_cvt_pk_bf16_f32 v78, v70, v71
	v_lshl_add_u64 v[80:81], s[56:57], 0, v[130:131]
	v_add_f32_e32 v76, 1.0, v76
	v_add_f32_e32 v77, 1.0, v77
	v_rcp_f32_e32 v76, v76
	v_rcp_f32_e32 v77, v77
	v_mfma_f32_16x16x32_bf16 v[14:17], v[160:163], v[146:149], v[14:17]
	s_add_u32 s56, s56, 0xfffe0000
	s_addc_u32 s57, s57, -1
	v_pk_mul_f32 v[74:75], v[76:77], v[74:75]
	v_mfma_f32_16x16x32_bf16 v[26:29], v[160:163], v[156:159], v[26:29]
	v_mul_f32_e64 v74, v74, v72
	v_mul_f32_e64 v75, v75, v73
	ds_read_b128 v[70:73], v0 offset:4096
	v_cvt_pk_bf16_f32 v79, v74, v75
	ds_read_b128 v[74:77], v0 offset:4160
	global_store_dwordx2 v[80:81], v[78:79], off
	v_mfma_f32_16x16x32_bf16 v[38:41], v[164:167], v[146:149], v[38:41]
	s_waitcnt lgkmcnt(1)
	v_mul_f32_e32 v70, 0x3fb8aa3b, v70
	v_exp_f32_e32 v82, v70
	v_mul_f32_e32 v83, 0x3fb8aa3b, v71
	v_mul_f32_e32 v70, 0x3fb8aa3b, v72
	v_mul_f32_e32 v71, 0x3fb8aa3b, v73
	v_exp_f32_e32 v70, v70
	v_exp_f32_e32 v71, v71
	v_exp_f32_e32 v83, v83
	v_mfma_f32_16x16x32_bf16 v[50:53], v[164:167], v[156:159], v[50:53]
	s_add_u32 s58, s58, 0xfffe0000
	v_pk_mul_f32 v[32:33], v[32:33], v[70:71]
	v_pk_mul_f32 v[8:9], v[8:9], v[70:71]
	s_waitcnt lgkmcnt(0)
	v_mul_f32_e32 v70, 0x3fb8aa3b, v74
	v_mul_f32_e32 v71, 0x3fb8aa3b, v76
	v_exp_f32_e32 v78, v70
	v_mul_f32_e32 v70, 0x3fb8aa3b, v75
	v_exp_f32_e32 v80, v71
	v_mul_f32_e32 v71, 0x3fb8aa3b, v77
	v_exp_f32_e32 v81, v71
	v_exp_f32_e32 v79, v70
	ds_read_b128 v[70:73], v0 offset:4224
	ds_read_b128 v[74:77], v0 offset:4288
	v_pk_mul_f32 v[30:31], v[30:31], v[82:83]
	v_pk_mul_f32 v[6:7], v[6:7], v[82:83]
	v_pk_mul_f32 v[12:13], v[12:13], v[80:81]
	s_waitcnt lgkmcnt(1)
	v_mul_f32_e32 v70, 0x3fb8aa3b, v70
	v_exp_f32_e32 v82, v70
	v_mul_f32_e32 v83, 0x3fb8aa3b, v71
	v_mul_f32_e32 v70, 0x3fb8aa3b, v72
	v_mul_f32_e32 v71, 0x3fb8aa3b, v73
	v_exp_f32_e32 v70, v70
	v_exp_f32_e32 v71, v71
	v_pk_mul_f32 v[10:11], v[10:11], v[78:79]
	v_pk_mul_f32 v[20:21], v[20:21], v[80:81]
	v_pk_mul_f32 v[18:19], v[18:19], v[78:79]
	v_pk_mul_f32 v[16:17], v[16:17], v[70:71]
	v_pk_mul_f32 v[28:29], v[28:29], v[70:71]
	s_waitcnt lgkmcnt(0)
	v_mul_f32_e32 v70, 0x3fb8aa3b, v74
	v_mul_f32_e32 v71, 0x3fb8aa3b, v76
	v_exp_f32_e32 v78, v70
	v_mul_f32_e32 v70, 0x3fb8aa3b, v75
	v_exp_f32_e32 v80, v71
	v_mul_f32_e32 v71, 0x3fb8aa3b, v77
	v_exp_f32_e32 v81, v71
	v_exp_f32_e32 v79, v70
	ds_read_b128 v[70:73], v0 offset:4352
	ds_read_b128 v[74:77], v0 offset:4416
	v_exp_f32_e32 v83, v83
	v_pk_mul_f32 v[40:41], v[40:41], v[80:81]
	v_pk_mul_f32 v[38:39], v[38:39], v[78:79]
	s_waitcnt lgkmcnt(1)
	v_mul_f32_e32 v70, 0x3fb8aa3b, v70
	v_pk_mul_f32 v[14:15], v[14:15], v[82:83]
	v_pk_mul_f32 v[26:27], v[26:27], v[82:83]
	v_exp_f32_e32 v82, v70
	v_mul_f32_e32 v83, 0x3fb8aa3b, v71
	v_mul_f32_e32 v70, 0x3fb8aa3b, v72
	v_mul_f32_e32 v71, 0x3fb8aa3b, v73
	v_exp_f32_e32 v70, v70
	v_exp_f32_e32 v71, v71
	v_pk_mul_f32 v[52:53], v[52:53], v[80:81]
	v_pk_mul_f32 v[50:51], v[50:51], v[78:79]
	v_mfma_f32_16x16x32_bf16 v[46:49], v[88:91], v[92:95], v[46:49]
	v_mul_f32_e64 v24, v24, v70
	v_mul_f32_e64 v25, v25, v71
	v_pk_mul_f32 v[36:37], v[36:37], v[70:71]
	s_waitcnt lgkmcnt(0)
	v_mul_f32_e32 v70, 0x3fb8aa3b, v74
	v_mul_f32_e32 v71, 0x3fb8aa3b, v76
	v_exp_f32_e32 v78, v70
	v_mul_f32_e32 v70, 0x3fb8aa3b, v75
	v_exp_f32_e32 v80, v71
	v_mul_f32_e32 v71, 0x3fb8aa3b, v77
	v_exp_f32_e32 v81, v71
	v_exp_f32_e32 v79, v70
	ds_read_b128 v[70:73], v0 offset:4480
	ds_read_b128 v[74:77], v0 offset:4544
	v_mfma_f32_16x16x32_bf16 v[62:65], v[88:91], v[96:99], v[62:65]
	v_exp_f32_e32 v83, v83
	s_addc_u32 s59, s59, -1
	s_waitcnt lgkmcnt(1)
	v_mul_f32_e32 v0, 0x3fb8aa3b, v70
	v_exp_f32_e32 v70, v0
	v_mul_f32_e32 v0, 0x3fb8aa3b, v71
	v_mul_f32_e32 v71, 0x3fb8aa3b, v72
	v_mfma_f32_16x16x32_bf16 v[58:61], v[100:103], v[92:95], v[58:61]
	v_exp_f32_e32 v72, v71
	v_mul_f32_e32 v71, 0x3fb8aa3b, v73
	v_exp_f32_e32 v73, v71
	v_mfma_f32_16x16x32_bf16 v[66:69], v[100:103], v[96:99], v[66:69]
	v_exp_f32_e32 v71, v0
	s_waitcnt lgkmcnt(0)
	v_mul_f32_e32 v0, 0x3fb8aa3b, v74
	v_exp_f32_e32 v74, v0
	v_mul_f32_e32 v0, 0x3fb8aa3b, v75
	v_mul_f32_e32 v75, 0x3fb8aa3b, v76
	v_exp_f32_e32 v76, v75
	v_mul_f32_e32 v75, 0x3fb8aa3b, v77
	v_mfma_f32_16x16x32_bf16 v[46:49], v[136:139], v[146:149], v[46:49]
	v_exp_f32_e32 v77, v75
	v_exp_f32_e32 v75, v0
	v_pk_mul_f32 v[22:23], v[22:23], v[82:83]
	v_mfma_f32_16x16x32_bf16 v[62:65], v[136:139], v[156:159], v[62:65]
	v_mul_f32_e64 v34, v34, v82
	v_mul_f32_e64 v35, v35, v83
	v_pk_mul_f32 v[44:45], v[44:45], v[80:81]
	v_pk_mul_f32 v[42:43], v[42:43], v[78:79]
	v_mfma_f32_16x16x32_bf16 v[58:61], v[142:145], v[146:149], v[58:61]
	v_mul_f32_e64 v56, v56, v80
	v_mul_f32_e64 v57, v57, v81
	v_pk_mul_f32 v[54:55], v[54:55], v[78:79]
	v_pk_mul_f32 v[48:49], v[48:49], v[72:73]
	v_mfma_f32_16x16x32_bf16 v[66:69], v[142:145], v[156:159], v[66:69]
	v_mul_f32_e64 v46, v46, v70
	v_mul_f32_e64 v47, v47, v71
	v_pk_mul_f32 v[64:65], v[64:65], v[72:73]
	v_pk_mul_f32 v[62:63], v[62:63], v[70:71]
	v_pk_mul_f32 v[60:61], v[60:61], v[76:77]
	v_pk_mul_f32 v[58:59], v[58:59], v[74:75]
	s_nop 1
	v_pk_mul_f32 v[68:69], v[68:69], v[76:77]
	s_cmp_lg_u32 s75, 8
	v_pk_mul_f32 v[66:67], v[66:67], v[74:75]
	s_cbranch_scc0 .LBB0_654
.LBB0_680:
	s_add_u32 s72, s48, s60
	s_addc_u32 s73, s70, s61
	s_and_b32 s67, s75, 1
	s_cmp_eq_u32 s67, 0
	s_cselect_b64 s[64:65], -1, 0
	s_and_b64 s[62:63], s[64:65], exec
	s_cselect_b32 s55, 0xf0, s69
	v_add3_u32 v105, s55, v177, v175
	ds_read2_b32 v[102:103], v105 offset1:4
	ds_read2_b32 v[136:137], v105 offset0:8 offset1:12
	s_waitcnt lgkmcnt(1)
	v_mfma_f32_16x16x4_f32 v[106:109], v102, v219, 0
	ds_read2_b32 v[140:141], v105 offset0:128 offset1:132
	s_nop 0
	v_mfma_f32_16x16x4_f32 v[106:109], v103, v220, v[106:109]
	s_waitcnt lgkmcnt(1)
	v_mfma_f32_16x16x4_f32 v[106:109], v136, v221, v[106:109]
	s_nop 0
	v_mfma_f32_16x16x4_f32 v[106:109], v137, v222, v[106:109]
	ds_read2_b32 v[136:137], v105 offset0:64 offset1:68
	s_nop 0
	s_nop 7
	v_add_f32_e32 v102, v223, v106
	v_min_f32_e32 v0, 0, v102
	v_mul_f32_e64 v102, |v102|, s97
	v_exp_f32_e32 v102, v102
	v_add_f32_e32 v103, v223, v107
	v_add_f32_e32 v104, v223, v108
	v_add_f32_e32 v106, v223, v109
	v_add_f32_e32 v102, 1.0, v102
	v_log_f32_e32 v102, v102
	s_nop 0
	v_fmac_f32_e32 v0, 0xbf317218, v102
	v_min_f32_e32 v102, 0, v103
	v_mul_f32_e64 v103, |v103|, s97
	v_exp_f32_e32 v103, v103
	s_nop 0
	v_add_f32_e32 v103, 1.0, v103
	v_log_f32_e32 v103, v103
	s_nop 0
	v_fmac_f32_e32 v102, 0xbf317218, v103
	v_min_f32_e32 v103, 0, v104
	v_mul_f32_e64 v104, |v104|, s97
	v_exp_f32_e32 v104, v104
	s_nop 0
	v_add_f32_e32 v104, 1.0, v104
	v_log_f32_e32 v104, v104
	s_nop 0
	v_fmac_f32_e32 v103, 0xbf317218, v104
	v_min_f32_e32 v104, 0, v106
	v_mul_f32_e64 v106, |v106|, s97
	v_exp_f32_e32 v106, v106
	s_nop 0
	v_add_f32_e32 v106, 1.0, v106
	v_log_f32_e32 v106, v106
	s_nop 0
	v_fmac_f32_e32 v104, 0xbf317218, v106
	s_waitcnt lgkmcnt(0)
	v_mfma_f32_16x16x4_f32 v[106:109], v136, v219, 0
	v_mfma_f32_16x16x4_f32 v[106:109], v137, v220, v[106:109]
	ds_read2_b32 v[136:137], v105 offset0:72 offset1:76
	s_waitcnt lgkmcnt(0)
	v_mfma_f32_16x16x4_f32 v[106:109], v136, v221, v[106:109]
	v_mfma_f32_16x16x4_f32 v[106:109], v137, v222, v[106:109]
	s_nop 9
	v_add_f32_e32 v136, v223, v106
	v_min_f32_e32 v106, 0, v136
	v_mul_f32_e64 v136, |v136|, s97
	v_exp_f32_e32 v136, v136
	s_nop 0
	v_add_f32_e32 v136, 1.0, v136
	v_log_f32_e32 v136, v136
	s_nop 0
	v_fmac_f32_e32 v106, 0xbf317218, v136
	v_add_f32_e32 v136, v223, v107
	v_min_f32_e32 v107, 0, v136
	v_mul_f32_e64 v136, |v136|, s97
	v_exp_f32_e32 v136, v136
	s_nop 0
	v_add_f32_e32 v136, 1.0, v136
	v_log_f32_e32 v136, v136
	s_nop 0
	v_fmac_f32_e32 v107, 0xbf317218, v136
	v_add_f32_e32 v136, v223, v108
	v_min_f32_e32 v108, 0, v136
	v_mul_f32_e64 v136, |v136|, s97
	v_exp_f32_e32 v136, v136
	s_nop 0
	v_add_f32_e32 v136, 1.0, v136
	v_log_f32_e32 v136, v136
	s_nop 0
	v_fmac_f32_e32 v108, 0xbf317218, v136
	v_add_f32_e32 v136, v223, v109
	v_min_f32_e32 v109, 0, v136
	v_mul_f32_e64 v136, |v136|, s97
	v_exp_f32_e32 v136, v136
	s_nop 0
	v_add_f32_e32 v136, 1.0, v136
	v_log_f32_e32 v136, v136
	s_nop 0
	v_fmac_f32_e32 v109, 0xbf317218, v136
	v_mfma_f32_16x16x4_f32 v[136:139], v140, v219, 0
	v_mfma_f32_16x16x4_f32 v[136:139], v141, v220, v[136:139]
	ds_read2_b32 v[140:141], v105 offset0:136 offset1:140
	s_waitcnt lgkmcnt(0)
	v_mfma_f32_16x16x4_f32 v[136:139], v140, v221, v[136:139]
	v_mfma_f32_16x16x4_f32 v[136:139], v141, v222, v[136:139]
	ds_read2_b32 v[140:141], v105 offset0:192 offset1:196
	s_nop 8
	v_add_f32_e32 v136, v223, v136
	v_min_f32_e32 v142, 0, v136
	v_mul_f32_e64 v136, |v136|, s97
	v_exp_f32_e32 v136, v136
	s_nop 0
	v_add_f32_e32 v136, 1.0, v136
	v_log_f32_e32 v136, v136
	s_nop 0
	v_fmac_f32_e32 v142, 0xbf317218, v136
	v_add_f32_e32 v136, v223, v137
	v_min_f32_e32 v143, 0, v136
	v_mul_f32_e64 v136, |v136|, s97
	v_exp_f32_e32 v136, v136
	s_nop 0
	v_add_f32_e32 v136, 1.0, v136
	v_log_f32_e32 v136, v136
	s_nop 0
	v_fmac_f32_e32 v143, 0xbf317218, v136
	v_add_f32_e32 v136, v223, v138
	v_min_f32_e32 v144, 0, v136
	v_mul_f32_e64 v136, |v136|, s97
	v_exp_f32_e32 v136, v136
	s_nop 0
	v_add_f32_e32 v136, 1.0, v136
	v_log_f32_e32 v136, v136
	s_nop 0
	v_fmac_f32_e32 v144, 0xbf317218, v136
	v_add_f32_e32 v136, v223, v139
	v_min_f32_e32 v145, 0, v136
	v_mul_f32_e64 v136, |v136|, s97
	v_exp_f32_e32 v136, v136
	s_nop 0
	v_add_f32_e32 v136, 1.0, v136
	v_log_f32_e32 v136, v136
	s_nop 0
	v_fmac_f32_e32 v145, 0xbf317218, v136
	s_waitcnt lgkmcnt(0)
	v_mfma_f32_16x16x4_f32 v[136:139], v140, v219, 0
	v_mfma_f32_16x16x4_f32 v[136:139], v141, v220, v[136:139]
	ds_read2_b32 v[140:141], v105 offset0:200 offset1:204
	s_waitcnt lgkmcnt(0)
	v_mfma_f32_16x16x4_f32 v[136:139], v140, v221, v[136:139]
	v_mfma_f32_16x16x4_f32 v[136:139], v141, v222, v[136:139]
	s_nop 9
	v_add_f32_e32 v105, v223, v136
	v_min_f32_e32 v136, 0, v105
	v_mul_f32_e64 v105, |v105|, s97
	v_exp_f32_e32 v105, v105
	s_nop 0
	v_add_f32_e32 v105, 1.0, v105
	v_log_f32_e32 v105, v105
	s_nop 0
	v_fmac_f32_e32 v136, 0xbf317218, v105
	v_add_f32_e32 v105, v223, v137
	v_min_f32_e32 v137, 0, v105
	v_mul_f32_e64 v105, |v105|, s97
	v_exp_f32_e32 v105, v105
	s_nop 0
	v_add_f32_e32 v105, 1.0, v105
	v_log_f32_e32 v105, v105
	s_nop 0
	v_fmac_f32_e32 v137, 0xbf317218, v105
	v_add_f32_e32 v105, v223, v138
	v_min_f32_e32 v138, 0, v105
	v_mul_f32_e64 v105, |v105|, s97
	v_exp_f32_e32 v105, v105
	s_nop 0
	v_add_f32_e32 v105, 1.0, v105
	v_log_f32_e32 v105, v105
	s_nop 0
	v_fmac_f32_e32 v138, 0xbf317218, v105
	v_add_f32_e32 v105, v223, v139
	v_min_f32_e32 v139, 0, v105
	v_mul_f32_e64 v105, |v105|, s97
	v_exp_f32_e32 v105, v105
	s_nop 0
	v_add_f32_e32 v105, 1.0, v105
	v_log_f32_e32 v105, v105
	s_nop 0
	v_fmac_f32_e32 v139, 0xbf317218, v105
	v_fma_f32 v105, v139, s0, 0
	v_fmamk_f32 v138, v138, 0x3d800000, v105
	v_fmamk_f32 v137, v137, 0x3d800000, v138
	v_fmamk_f32 v136, v136, 0x3d800000, v137
	v_fmamk_f32 v139, v145, 0x3d800000, v136
	v_fmamk_f32 v140, v144, 0x3d800000, v139
	v_fmamk_f32 v141, v143, 0x3d800000, v140
	v_fmamk_f32 v142, v142, 0x3d800000, v141
	v_fmamk_f32 v109, v109, 0x3d800000, v142
	v_fmamk_f32 v108, v108, 0x3d800000, v109
	v_fmamk_f32 v107, v107, 0x3d800000, v108
	v_fmamk_f32 v106, v106, 0x3d800000, v107
	v_fmamk_f32 v104, v104, 0x3d800000, v106
	v_fmamk_f32 v103, v103, 0x3d800000, v104
	v_fmamk_f32 v102, v102, 0x3d800000, v103
	v_fmamk_f32 v0, v0, 0x3d800000, v102
	ds_bpermute_b32 v144, v188, v0
	ds_bpermute_b32 v145, v189, v0
	ds_bpermute_b32 v143, v187, v0
	s_waitcnt lgkmcnt(2)
	v_cndmask_b32_e64 v144, 0, v144, s[28:29]
	s_waitcnt lgkmcnt(1)
	v_cndmask_b32_e64 v145, v145, 0, s[8:9]
	v_add_f32_e32 v144, v144, v145
	s_waitcnt lgkmcnt(0)
	v_cndmask_b32_e64 v143, 0, v143, s[4:5]
	v_add_f32_e32 v143, v143, v144
	v_add_f32_e32 v0, v143, v0
	v_add_f32_e32 v102, v143, v102
	ds_write2st64_b32 v200, v0, v102 offset0:24 offset1:26
	v_add_f32_e32 v0, v143, v103
	v_add_f32_e32 v102, v143, v104
	ds_write2st64_b32 v200, v0, v102 offset0:28 offset1:30
	v_add_f32_e32 v0, v143, v106
	v_add_f32_e32 v102, v143, v107
	ds_write2st64_b32 v200, v0, v102 offset0:32 offset1:34
	v_add_f32_e32 v0, v143, v108
	v_add_f32_e32 v102, v143, v109
	ds_write2st64_b32 v200, v0, v102 offset0:36 offset1:38
	v_add_f32_e32 v0, v143, v142
	v_add_f32_e32 v102, v143, v141
	ds_write2st64_b32 v200, v0, v102 offset0:40 offset1:42
	v_add_f32_e32 v0, v143, v140
	v_add_f32_e32 v102, v143, v139
	ds_write2st64_b32 v200, v0, v102 offset0:44 offset1:46
	v_add_f32_e32 v0, v143, v136
	v_add_f32_e32 v102, v143, v137
	ds_write2st64_b32 v200, v0, v102 offset0:48 offset1:50
	v_add_f32_e32 v0, v143, v138
	v_add_f32_e32 v102, v143, v105
	ds_write2st64_b32 v200, v0, v102 offset0:52 offset1:54
	s_waitcnt lgkmcnt(0)
	s_barrier
	s_and_saveexec_b64 s[62:63], s[10:11]
	s_cbranch_execz .LBB0_682
	ds_read_b32 v0, v178 offset:6144
	v_lshl_add_u32 v102, s67, 9, v178
	s_waitcnt lgkmcnt(0)
	ds_write_b32 v102, v0 offset:4096

.LBB0_689:
	ds_read_b128 v[102:105], v201 offset:6144
	ds_read_b128 v[106:109], v201 offset:6160
	s_waitcnt vmcnt(6)
	v_lshlrev_b32_e32 v138, 16, v196
	v_and_b32_e32 v139, 0xffff0000, v196
	s_waitcnt lgkmcnt(1)
	v_mul_f32_e32 v0, 0xbfb8aa3b, v102
	v_exp_f32_e32 v136, v0
	v_mul_f32_e32 v0, 0xbfb8aa3b, v103
	v_exp_f32_e32 v137, v0
	v_mul_f32_e32 v0, 0xbfb8aa3b, v104
	v_pk_mul_f32 v[136:137], v[136:137], v[138:139]
	s_nop 0
	v_cvt_pk_bf16_f32 v98, v136, v137
	v_exp_f32_e32 v136, v0
	v_mul_f32_e32 v0, 0xbfb8aa3b, v105
	v_exp_f32_e32 v137, v0
	v_lshlrev_b32_e32 v138, 16, v197
	v_and_b32_e32 v139, 0xffff0000, v197
	s_waitcnt lgkmcnt(0)
	v_mul_f32_e32 v0, 0xbfb8aa3b, v106
	v_pk_mul_f32 v[136:137], v[136:137], v[138:139]
	v_lshlrev_b32_e32 v138, 16, v198
	v_cvt_pk_bf16_f32 v99, v136, v137
	v_exp_f32_e32 v136, v0
	v_mul_f32_e32 v0, 0xbfb8aa3b, v107
	v_exp_f32_e32 v137, v0
	v_and_b32_e32 v139, 0xffff0000, v198
	v_mul_f32_e32 v0, 0xbfb8aa3b, v108
	v_pk_mul_f32 v[136:137], v[136:137], v[138:139]
	s_nop 0
	v_cvt_pk_bf16_f32 v100, v136, v137
	v_exp_f32_e32 v136, v0
	v_mul_f32_e32 v0, 0xbfb8aa3b, v109
	v_exp_f32_e32 v137, v0
	v_lshlrev_b32_e32 v138, 16, v199
	v_and_b32_e32 v139, 0xffff0000, v199
	v_mul_f32_e32 v0, 0x3fb8aa3b, v102
	v_pk_mul_f32 v[136:137], v[136:137], v[138:139]
	s_nop 0
	v_cvt_pk_bf16_f32 v101, v136, v137
	ds_write_b128 v181, v[98:101] offset:56320
	v_exp_f32_e32 v98, v0
	v_mul_f32_e32 v0, 0x3fb8aa3b, v103
	v_exp_f32_e32 v99, v0
	v_lshlrev_b32_e32 v100, 16, v192
	v_and_b32_e32 v101, 0xffff0000, v192
	v_mul_f32_e32 v0, 0x3fb8aa3b, v104
	v_pk_mul_f32 v[98:99], v[98:99], s[50:51] op_sel_hi:[1,0]
	s_waitcnt vmcnt(4)
	v_lshlrev_b32_e32 v104, 16, v236
	v_pk_mul_f32 v[98:99], v[98:99], v[100:101]
	v_lshlrev_b32_e32 v100, 16, v193
	v_cvt_pk_bf16_f32 v94, v98, v99
	v_exp_f32_e32 v98, v0
	v_mul_f32_e32 v0, 0x3fb8aa3b, v105
	v_exp_f32_e32 v99, v0
	v_and_b32_e32 v101, 0xffff0000, v193
	v_mul_f32_e32 v0, 0x3fb8aa3b, v106
	v_and_b32_e32 v105, 0xffff0000, v236
	v_pk_mul_f32 v[98:99], v[98:99], s[50:51] op_sel_hi:[1,0]
	s_nop 0
	v_pk_mul_f32 v[98:99], v[98:99], v[100:101]
	v_lshlrev_b32_e32 v100, 16, v194
	v_cvt_pk_bf16_f32 v95, v98, v99
	v_exp_f32_e32 v98, v0
	v_mul_f32_e32 v0, 0x3fb8aa3b, v107
	v_exp_f32_e32 v99, v0
	v_and_b32_e32 v101, 0xffff0000, v194
	v_mul_f32_e32 v0, 0x3fb8aa3b, v108
	v_pk_mul_f32 v[98:99], v[98:99], s[50:51] op_sel_hi:[1,0]
	s_nop 0
	v_pk_mul_f32 v[98:99], v[98:99], v[100:101]
	v_lshlrev_b32_e32 v100, 16, v195
	v_cvt_pk_bf16_f32 v96, v98, v99
	v_exp_f32_e32 v98, v0
	v_mul_f32_e32 v0, 0x3fb8aa3b, v109
	v_exp_f32_e32 v99, v0
	v_and_b32_e32 v101, 0xffff0000, v195
	v_pk_mul_f32 v[98:99], v[98:99], s[50:51] op_sel_hi:[1,0]
	s_nop 0
	v_pk_mul_f32 v[98:99], v[98:99], v[100:101]
	s_nop 0
	v_cvt_pk_bf16_f32 v97, v98, v99
	ds_write_b128 v181, v[94:97] offset:38912
	ds_read_b128 v[94:97], v202 offset:6144
	ds_read_b128 v[98:101], v202 offset:6160
	s_waitcnt lgkmcnt(1)
	v_mul_f32_e32 v0, 0xbfb8aa3b, v94
	v_exp_f32_e32 v102, v0
	v_mul_f32_e32 v0, 0xbfb8aa3b, v95
	v_exp_f32_e32 v103, v0
	v_mul_f32_e32 v0, 0xbfb8aa3b, v96
	v_pk_mul_f32 v[102:103], v[102:103], v[104:105]
	s_nop 0
	v_cvt_pk_bf16_f32 v90, v102, v103
	v_exp_f32_e32 v102, v0
	v_mul_f32_e32 v0, 0xbfb8aa3b, v97
	v_exp_f32_e32 v103, v0
	v_lshlrev_b32_e32 v104, 16, v237
	v_and_b32_e32 v105, 0xffff0000, v237
	s_waitcnt lgkmcnt(0)
	v_mul_f32_e32 v0, 0xbfb8aa3b, v98
	v_pk_mul_f32 v[102:103], v[102:103], v[104:105]
	v_lshlrev_b32_e32 v104, 16, v238
	v_cvt_pk_bf16_f32 v91, v102, v103
	v_exp_f32_e32 v102, v0
	v_mul_f32_e32 v0, 0xbfb8aa3b, v99
	v_exp_f32_e32 v103, v0
	v_and_b32_e32 v105, 0xffff0000, v238
	v_mul_f32_e32 v0, 0xbfb8aa3b, v100
	v_pk_mul_f32 v[102:103], v[102:103], v[104:105]
	s_nop 0
	v_cvt_pk_bf16_f32 v92, v102, v103
	v_exp_f32_e32 v102, v0
	v_mul_f32_e32 v0, 0xbfb8aa3b, v101
	v_exp_f32_e32 v103, v0
	v_lshlrev_b32_e32 v104, 16, v239
	v_and_b32_e32 v105, 0xffff0000, v239
	v_mul_f32_e32 v0, 0x3fb8aa3b, v94
	v_pk_mul_f32 v[102:103], v[102:103], v[104:105]
	s_nop 0
	v_cvt_pk_bf16_f32 v93, v102, v103
	ds_write_b128 v182, v[90:93] offset:56320
	v_exp_f32_e32 v90, v0
	v_mul_f32_e32 v0, 0x3fb8aa3b, v95
	v_exp_f32_e32 v91, v0
	v_lshlrev_b32_e32 v92, 16, v232
	v_and_b32_e32 v93, 0xffff0000, v232
	v_mul_f32_e32 v0, 0x3fb8aa3b, v96
	v_pk_mul_f32 v[90:91], v[90:91], s[50:51] op_sel_hi:[1,0]
	s_nop 0
	v_pk_mul_f32 v[90:91], v[90:91], v[92:93]
	v_lshlrev_b32_e32 v92, 16, v233
	v_cvt_pk_bf16_f32 v70, v90, v91
	v_exp_f32_e32 v90, v0
	v_mul_f32_e32 v0, 0x3fb8aa3b, v97
	v_exp_f32_e32 v91, v0
	v_and_b32_e32 v93, 0xffff0000, v233
	v_mul_f32_e32 v0, 0x3fb8aa3b, v98
	v_pk_mul_f32 v[90:91], v[90:91], s[50:51] op_sel_hi:[1,0]
	s_nop 0
	v_pk_mul_f32 v[90:91], v[90:91], v[92:93]
	v_lshlrev_b32_e32 v92, 16, v234
	v_cvt_pk_bf16_f32 v71, v90, v91
	v_exp_f32_e32 v90, v0
	v_mul_f32_e32 v0, 0x3fb8aa3b, v99
	v_exp_f32_e32 v91, v0
	v_and_b32_e32 v93, 0xffff0000, v234
	v_mul_f32_e32 v0, 0x3fb8aa3b, v100
	v_pk_mul_f32 v[90:91], v[90:91], s[50:51] op_sel_hi:[1,0]
	s_nop 0
	v_pk_mul_f32 v[90:91], v[90:91], v[92:93]
	v_lshlrev_b32_e32 v92, 16, v235
	v_cvt_pk_bf16_f32 v72, v90, v91
	v_exp_f32_e32 v90, v0
	v_mul_f32_e32 v0, 0x3fb8aa3b, v101
	v_exp_f32_e32 v91, v0
	v_and_b32_e32 v93, 0xffff0000, v235
	v_pk_mul_f32 v[90:91], v[90:91], s[50:51] op_sel_hi:[1,0]
	s_nop 0
	v_pk_mul_f32 v[90:91], v[90:91], v[92:93]
	s_nop 0
	v_cvt_pk_bf16_f32 v73, v90, v91
	ds_write_b128 v182, v[70:73] offset:38912
	s_waitcnt vmcnt(3)
	ds_write_b128 v203, v[244:247]
	s_waitcnt vmcnt(2)
	ds_write_b128 v204, v[248:251]
	s_waitcnt vmcnt(1)
	ds_write_b128 v203, v[252:255] offset:16896
	s_waitcnt vmcnt(0)
	ds_write_b128 v205, v[170:173]
	v_lshl_add_u64 v[70:71], s[58:59], 0, v[116:117]
	v_lshl_add_u64 v[72:73], s[58:59], 0, v[120:121]
	v_lshl_add_u64 v[74:75], s[58:59], 0, v[122:123]
	global_load_dwordx2 v[156:157], v[70:71], off
	global_load_dwordx2 v[152:153], v[70:71], off offset:32
	global_load_dwordx2 v[148:149], v[72:73], off
	global_load_dwordx2 v[146:147], v[74:75], off
	v_lshl_add_u64 v[70:71], s[58:59], 0, v[124:125]
	v_lshl_add_u64 v[72:73], s[58:59], 0, v[126:127]
	v_lshl_add_u64 v[74:75], s[58:59], 0, v[128:129]
	v_lshl_add_u64 v[76:77], s[58:59], 0, v[130:131]
	global_load_dwordx2 v[144:145], v[70:71], off
	global_load_dwordx2 v[142:143], v[72:73], off
	global_load_dwordx2 v[138:139], v[74:75], off
	global_load_dwordx2 v[136:137], v[76:77], off
	s_waitcnt lgkmcnt(0)
	s_barrier
	ds_read_b128 v[70:73], v206 offset:56320
	ds_read_b128 v[74:77], v180 offset:38912
	ds_read_b128 v[78:81], v206 offset:56384
	ds_read_b128 v[82:85], v180 offset:38976
	s_waitcnt lgkmcnt(2)
	v_mfma_f32_16x16x32_bf16 v[70:73], v[70:73], v[74:77], 0
	v_mov_b32_e32 v0, s49
	v_cvt_pk_bf16_f32 v166, v62, v63
	v_cvt_pk_bf16_f32 v167, v64, v65
	s_waitcnt lgkmcnt(0)
	v_mfma_f32_16x16x32_bf16 v[70:73], v[78:81], v[82:85], v[70:73]
	ds_read_b128 v[78:81], v206 offset:56448
	ds_read_b128 v[86:89], v180 offset:39040
	v_cvt_pk_bf16_f32 v168, v66, v67
	v_cvt_pk_bf16_f32 v169, v68, v69
	s_waitcnt lgkmcnt(0)
	v_mfma_f32_16x16x32_bf16 v[70:73], v[78:81], v[86:89], v[70:73]
	ds_read_b128 v[78:81], v206 offset:56512
	ds_read_b128 v[90:93], v180 offset:39104
	s_add_u32 s55, s72, s68
	s_addc_u32 s63, s73, 0
	s_waitcnt lgkmcnt(0)
	v_mfma_f32_16x16x32_bf16 v[70:73], v[78:81], v[90:93], v[70:73]
	s_add_u32 s62, s55, 0xafc1000
	s_addc_u32 s63, s63, 0
	s_waitcnt vmcnt(7)
	v_lshlrev_b32_e32 v224, 16, v156
	s_nop 3
	v_cndmask_b32_e64 v0, v70, v0, s[14:15]
	v_cndmask_b32_e64 v70, v71, 0, s[30:31]
	v_cndmask_b32_e64 v71, v72, 0, s[34:35]
	v_cndmask_b32_e64 v72, v73, 0, s[36:37]
	v_cvt_pk_bf16_f32 v70, v0, v70
	v_cvt_pk_bf16_f32 v71, v71, v72
	ds_write_b64 v207, v[70:71]
	ds_read_b128 v[70:73], v208 offset:56320
	s_waitcnt lgkmcnt(0)
	v_mfma_f32_16x16x32_bf16 v[70:73], v[70:73], v[74:77], 0
	ds_read_b128 v[74:77], v208 offset:56384
	v_mov_b32_e32 v0, s49
	v_and_b32_e32 v225, 0xffff0000, v156
	s_waitcnt lgkmcnt(0)
	v_mfma_f32_16x16x32_bf16 v[70:73], v[74:77], v[82:85], v[70:73]
	ds_read_b128 v[74:77], v208 offset:56448
	v_lshlrev_b32_e32 v156, 16, v157
	v_and_b32_e32 v157, 0xffff0000, v157
	s_waitcnt lgkmcnt(0)
	v_mfma_f32_16x16x32_bf16 v[70:73], v[74:77], v[86:89], v[70:73]
	ds_read_b128 v[74:77], v208 offset:56512
	s_waitcnt vmcnt(6)
	v_lshlrev_b32_e32 v226, 16, v152
	v_and_b32_e32 v227, 0xffff0000, v152
	s_waitcnt lgkmcnt(0)
	v_mfma_f32_16x16x32_bf16 v[70:73], v[74:77], v[90:93], v[70:73]
	v_lshlrev_b32_e32 v152, 16, v153
	v_and_b32_e32 v153, 0xffff0000, v153
	s_nop 5
	v_cndmask_b32_e64 v0, v70, v0, s[22:23]
	v_cndmask_b32_e64 v70, v71, 0, s[38:39]
	v_cndmask_b32_e64 v71, v72, 0, s[40:41]
	v_cndmask_b32_e64 v72, v73, 0, s[42:43]
	v_cvt_pk_bf16_f32 v70, v0, v70
	v_cvt_pk_bf16_f32 v71, v71, v72
	ds_write_b64 v209, v[70:71]
	s_waitcnt lgkmcnt(0)
	s_barrier
	ds_read_b64_tr_b16 v[72:73], v210 offset:2112
	ds_read_b64_tr_b16 v[70:71], v210
	ds_read_b64_tr_b16 v[74:75], v210 offset:32
	ds_read_b64_tr_b16 v[78:79], v210 offset:16896
	ds_read_b64_tr_b16 v[80:81], v210 offset:19008
	ds_read_b64_tr_b16 v[76:77], v210 offset:2144
	ds_read_b64_tr_b16 v[82:83], v210 offset:16928
	ds_read_b64_tr_b16 v[84:85], v210 offset:19040
	ds_read_b128 v[86:89], v211
	ds_read_b128 v[94:97], v211 offset:64
	ds_read_b128 v[102:105], v211 offset:2368
	s_waitcnt lgkmcnt(2)
	v_mfma_f32_16x16x32_bf16 v[90:93], v[70:73], v[86:89], 0
	ds_read_b128 v[158:161], v211 offset:4672
	v_mfma_f32_16x16x32_bf16 v[86:89], v[74:77], v[86:89], 0
	s_waitcnt lgkmcnt(2)
	v_mfma_f32_16x16x32_bf16 v[90:93], v[78:81], v[94:97], v[90:93]
	v_mfma_f32_16x16x32_bf16 v[86:89], v[82:85], v[94:97], v[86:89]
	ds_read_b128 v[94:97], v211 offset:2304
	s_waitcnt lgkmcnt(0)
	v_mfma_f32_16x16x32_bf16 v[98:101], v[70:73], v[94:97], 0
	v_mfma_f32_16x16x32_bf16 v[94:97], v[74:77], v[94:97], 0
	v_mfma_f32_16x16x32_bf16 v[98:101], v[78:81], v[102:105], v[98:101]
	v_mfma_f32_16x16x32_bf16 v[94:97], v[82:85], v[102:105], v[94:97]
	ds_read_b128 v[102:105], v211 offset:4608
	s_waitcnt lgkmcnt(0)
	v_mfma_f32_16x16x32_bf16 v[106:109], v[70:73], v[102:105], 0
	v_mfma_f32_16x16x32_bf16 v[102:105], v[74:77], v[102:105], 0
	v_mfma_f32_16x16x32_bf16 v[106:109], v[78:81], v[158:161], v[106:109]
	v_mfma_f32_16x16x32_bf16 v[102:105], v[82:85], v[158:161], v[102:105]
	ds_read_b128 v[158:161], v211 offset:6912
	s_waitcnt lgkmcnt(0)
	v_mfma_f32_16x16x32_bf16 v[70:73], v[70:73], v[158:161], 0
	v_mfma_f32_16x16x32_bf16 v[74:77], v[74:77], v[158:161], 0
	ds_read_b128 v[158:161], v211 offset:6976
	s_waitcnt lgkmcnt(0)
	v_mfma_f32_16x16x32_bf16 v[70:73], v[78:81], v[158:161], v[70:73]
	v_cvt_pk_bf16_f32 v78, v30, v31
	v_cvt_pk_bf16_f32 v79, v32, v33
	v_cvt_pk_bf16_f32 v80, v10, v11
	v_mfma_f32_16x16x32_bf16 v[74:77], v[82:85], v[158:161], v[74:77]
	v_cvt_pk_bf16_f32 v81, v12, v13
	v_cvt_pk_bf16_f32 v82, v6, v7
	v_cvt_pk_bf16_f32 v83, v8, v9
	v_cvt_pk_bf16_f32 v84, v18, v19
	v_cvt_pk_bf16_f32 v85, v20, v21
	ds_read2_b64 v[158:161], v215 offset1:4
	s_waitcnt lgkmcnt(0)
	v_mfma_f32_16x16x32_bf16 v[90:93], v[78:81], v[158:161], v[90:93]
	v_mfma_f32_16x16x32_bf16 v[86:89], v[82:85], v[158:161], v[86:89]
	ds_read2_b64 v[158:161], v216 offset0:32 offset1:36
	s_waitcnt lgkmcnt(0)
	v_mfma_f32_16x16x32_bf16 v[98:101], v[78:81], v[158:161], v[98:101]
	v_mfma_f32_16x16x32_bf16 v[94:97], v[82:85], v[158:161], v[94:97]
	ds_read2_b64 v[158:161], v217 offset0:64 offset1:68
	s_waitcnt lgkmcnt(0)
	v_mfma_f32_16x16x32_bf16 v[106:109], v[78:81], v[158:161], v[106:109]
	v_mfma_f32_16x16x32_bf16 v[102:105], v[82:85], v[158:161], v[102:105]
	ds_read2_b64 v[158:161], v218 offset0:96 offset1:100
	s_waitcnt lgkmcnt(0)
	v_mfma_f32_16x16x32_bf16 v[70:73], v[78:81], v[158:161], v[70:73]
	v_cvt_pk_bf16_f32 v78, v14, v15
	v_cvt_pk_bf16_f32 v79, v16, v17
	v_cvt_pk_bf16_f32 v80, v38, v39
	v_mfma_f32_16x16x32_bf16 v[74:77], v[82:85], v[158:161], v[74:77]
	v_cvt_pk_bf16_f32 v81, v40, v41
	v_cvt_pk_bf16_f32 v82, v26, v27
	v_cvt_pk_bf16_f32 v83, v28, v29
	v_cvt_pk_bf16_f32 v84, v50, v51
	v_cvt_pk_bf16_f32 v85, v52, v53
	ds_read2_b64 v[158:161], v215 offset0:8 offset1:12
	s_waitcnt lgkmcnt(0)
	v_mfma_f32_16x16x32_bf16 v[90:93], v[78:81], v[158:161], v[90:93]
	v_mfma_f32_16x16x32_bf16 v[86:89], v[82:85], v[158:161], v[86:89]
	ds_read2_b64 v[158:161], v216 offset0:40 offset1:44
	s_waitcnt lgkmcnt(0)
	v_mfma_f32_16x16x32_bf16 v[98:101], v[78:81], v[158:161], v[98:101]
	v_mfma_f32_16x16x32_bf16 v[94:97], v[82:85], v[158:161], v[94:97]
	ds_read2_b64 v[158:161], v217 offset0:72 offset1:76
	s_waitcnt lgkmcnt(0)
	v_mfma_f32_16x16x32_bf16 v[106:109], v[78:81], v[158:161], v[106:109]
	v_mfma_f32_16x16x32_bf16 v[102:105], v[82:85], v[158:161], v[102:105]
	ds_read2_b64 v[158:161], v218 offset0:104 offset1:108
	s_waitcnt lgkmcnt(0)
	v_mfma_f32_16x16x32_bf16 v[70:73], v[78:81], v[158:161], v[70:73]
	v_cvt_pk_bf16_f32 v78, v22, v23
	v_cvt_pk_bf16_f32 v79, v24, v25
	v_cvt_pk_bf16_f32 v80, v42, v43
	v_mfma_f32_16x16x32_bf16 v[74:77], v[82:85], v[158:161], v[74:77]
	v_cvt_pk_bf16_f32 v81, v44, v45
	v_cvt_pk_bf16_f32 v82, v34, v35
	v_cvt_pk_bf16_f32 v83, v36, v37
	v_cvt_pk_bf16_f32 v84, v54, v55
	v_cvt_pk_bf16_f32 v85, v56, v57
	ds_read2_b64 v[158:161], v215 offset0:16 offset1:20
	s_waitcnt lgkmcnt(0)
	v_mfma_f32_16x16x32_bf16 v[90:93], v[78:81], v[158:161], v[90:93]
	v_mfma_f32_16x16x32_bf16 v[86:89], v[82:85], v[158:161], v[86:89]
	ds_read2_b64 v[158:161], v216 offset0:48 offset1:52
	s_waitcnt lgkmcnt(0)
	v_mfma_f32_16x16x32_bf16 v[98:101], v[78:81], v[158:161], v[98:101]
	v_mfma_f32_16x16x32_bf16 v[94:97], v[82:85], v[158:161], v[94:97]
	ds_read2_b64 v[158:161], v217 offset0:80 offset1:84
	s_waitcnt lgkmcnt(0)
	v_mfma_f32_16x16x32_bf16 v[162:165], v[78:81], v[158:161], v[106:109]
	v_mfma_f32_16x16x32_bf16 v[158:161], v[82:85], v[158:161], v[102:105]
	s_nop 2
	ds_read2_b64 v[102:105], v218 offset0:112 offset1:116
	s_waitcnt lgkmcnt(0)
	v_mfma_f32_16x16x32_bf16 v[70:73], v[78:81], v[102:105], v[70:73]
	v_cvt_pk_bf16_f32 v78, v46, v47
	v_cvt_pk_bf16_f32 v79, v48, v49
	v_cvt_pk_bf16_f32 v80, v58, v59
	v_mfma_f32_16x16x32_bf16 v[74:77], v[82:85], v[102:105], v[74:77]
	v_cvt_pk_bf16_f32 v81, v60, v61
	ds_read2_b64 v[82:85], v215 offset0:24 offset1:28
	s_waitcnt lgkmcnt(0)
	v_mfma_f32_16x16x32_bf16 v[106:109], v[78:81], v[82:85], v[90:93]
	v_mfma_f32_16x16x32_bf16 v[102:105], v[166:169], v[82:85], v[86:89]
	ds_read2_b64 v[82:85], v216 offset0:56 offset1:60
	s_nop 5
	v_pk_add_f32 v[106:107], v[106:107], v[224:225]
	v_pk_add_f32 v[108:109], v[108:109], v[156:157]
	s_waitcnt lgkmcnt(0)
	v_mfma_f32_16x16x32_bf16 v[98:101], v[78:81], v[82:85], v[98:101]
	v_mul_f32_e64 v156, v106, v106
	v_mul_f32_e64 v157, v107, v107
	v_pk_mul_f32 v[224:225], v[108:109], v[108:109]
	v_add_f32_e32 v0, v156, v157
	v_mfma_f32_16x16x32_bf16 v[94:97], v[166:169], v[82:85], v[94:97]
	ds_read2_b64 v[82:85], v217 offset0:88 offset1:92
	v_pk_add_f32 v[102:103], v[102:103], v[226:227]
	v_add_f32_e32 v0, v224, v0
	s_waitcnt lgkmcnt(0)
	v_mfma_f32_16x16x32_bf16 v[86:89], v[166:169], v[82:85], v[158:161]
	v_add_f32_e64 v104, v104, v152
	v_add_f32_e64 v105, v105, v153
	s_nop 0
	ds_read2_b64 v[158:161], v218 offset0:120 offset1:124
	v_pk_mul_f32 v[152:153], v[102:103], v[102:103]
	v_mfma_f32_16x16x32_bf16 v[90:93], v[78:81], v[82:85], v[162:165]
	v_add_f32_e32 v0, v225, v0
	v_add_f32_e32 v0, v152, v0
	v_pk_mul_f32 v[226:227], v[104:105], v[104:105]
	s_waitcnt lgkmcnt(0)
	v_mfma_f32_16x16x32_bf16 v[82:85], v[78:81], v[158:161], v[70:73]
	v_add_f32_e32 v0, v153, v0
	v_add_f32_e32 v0, v226, v0
	v_add_f32_e32 v0, v227, v0
	v_lshl_add_u64 v[70:71], s[62:63], 0, v[118:119]
	v_add_co_u32_e32 v72, vcc, s81, v70
	v_mfma_f32_16x16x32_bf16 v[78:81], v[166:169], v[158:161], v[74:77]
	s_nop 0
	v_addc_co_u32_e32 v73, vcc, 0, v71, vcc
	global_load_dwordx2 v[168:169], v[70:71], off
	global_load_dwordx2 v[166:167], v[70:71], off offset:32
	global_load_dwordx2 v[164:165], v[72:73], off
	global_load_dwordx2 v[162:163], v[72:73], off offset:32
	v_add_co_u32_e32 v72, vcc, s95, v70
	ds_bpermute_b32 v152, v190, v0
	s_nop 0
	v_addc_co_u32_e32 v73, vcc, 0, v71, vcc
	v_add_co_u32_e32 v70, vcc, s96, v70
	global_load_dwordx2 v[160:161], v[72:73], off
	global_load_dwordx2 v[158:159], v[72:73], off offset:32
	v_addc_co_u32_e32 v71, vcc, 0, v71, vcc
	global_load_dwordx2 v[150:151], v[70:71], off
	global_load_dwordx2 v[140:141], v[70:71], off offset:32
	global_load_dwordx4 v[74:77], v[134:135], off
	s_nop 0
	global_load_dwordx4 v[70:73], v[134:135], off offset:64
	s_waitcnt lgkmcnt(0)
	v_add_f32_e32 v0, v0, v152
	ds_bpermute_b32 v152, v191, v0
	s_and_saveexec_b64 s[62:63], s[4:5]
	s_cbranch_execz .LBB0_691
	s_waitcnt lgkmcnt(0)
	v_add_f32_e32 v0, v0, v152
	ds_write_b32 v185, v0
